# grid barrier release: waiting workgroups poll the top-level generation word directly (one hop less), on top of static first tickets
# speedup vs baseline: 1.0053x; 1.0007x over previous
; DI unsigned xb_ld(unsigned* p)              { return __hip_atomic_load(p, __ATOMIC_RELAXED, __HIP_MEMORY_SCOPE_AGENT); }
; DI unsigned xb_add(unsigned* p, unsigned v) { return __hip_atomic_fetch_add(p, v, __ATOMIC_RELAXED, __HIP_MEMORY_SCOPE_AGENT); }
; #define XB_SPIN(cond, bar) do { unsigned _sp = 0; while (cond) { __builtin_amdgcn_s_sleep(1); \
;     if ((++_sp & 255u) == 0u) { if (xb_ld(&(bar)[XB_TMO])) break; if (_sp > XB_SPIN_CAP) { atomicAdd(&(bar)[XB_TMO], 1u); break; } } } } while (0)
; DI void xcd_barrier(unsigned* bar, volatile LAS unsigned* st, bool leader) {
;     ...
;         const unsigned old = xb_add(&bar[XB_XSUB(x)], 1u);
;         const unsigned gen = old / nloc;
;         if (old + 1u == (gen + 1u) * nloc) {
;             __builtin_amdgcn_fence(__ATOMIC_RELEASE, "agent");
;             asm volatile("s_waitcnt vmcnt(0)" ::: "memory");
;             const unsigned og = xb_add(&bar[XB_TOP], 1u);
;             const unsigned tg = og / nx;
;             if (og + 1u == (tg + 1u) * nx) xb_add(&bar[XB_TOPGEN], 1u);
;             else XB_SPIN(xb_ld(&bar[XB_TOPGEN]) == tg, bar);
;             __builtin_amdgcn_fence(__ATOMIC_ACQUIRE, "agent");
;             xb_add(&bar[XB_XGEN(x)], 1u);
;             asm volatile("s_waitcnt vmcnt(0)" ::: "memory");
;         } else {
;             XB_SPIN(xb_ld(&bar[XB_XGEN(x)]) == gen, bar);
.LBB0_195:
	s_or_b64 exec, exec, s[8:9]
	v_cvt_f32_u32_e32 v4, v2
	s_waitcnt vmcnt(0)
	v_readfirstlane_b32 s6, v3
	v_sub_u32_e32 v3, 0, v2
	v_rcp_iflag_f32_e32 v4, v4
	v_add_u32_e32 v5, s6, v1
	v_mul_f32_e32 v4, 0x4f7ffffe, v4
	v_cvt_u32_f32_e32 v4, v4
	v_mul_lo_u32 v1, v3, v4
	v_mul_hi_u32 v1, v4, v1
	v_add_u32_e32 v1, v4, v1
	v_mul_hi_u32 v1, v5, v1
	v_mul_lo_u32 v3, v1, v2
	v_sub_u32_e32 v3, v5, v3
	v_add_u32_e32 v4, 1, v1
	v_cmp_ge_u32_e32 vcc, v3, v2
	s_nop 1
	v_cndmask_b32_e32 v1, v1, v4, vcc
	v_sub_u32_e32 v4, v3, v2
	v_cndmask_b32_e32 v3, v3, v4, vcc
	v_add_u32_e32 v4, 1, v1
	v_cmp_ge_u32_e32 vcc, v3, v2
	v_add_u32_e32 v3, 1, v5
	s_nop 0
	v_cndmask_b32_e32 v1, v1, v4, vcc
	v_mul_lo_u32 v4, v2, v1
	v_add_u32_e32 v2, v4, v2
	v_cmp_ne_u32_e32 vcc, v3, v2
	s_and_saveexec_b64 s[6:7], vcc
	s_xor_b64 s[6:7], exec, s[6:7]
	s_cbranch_execz .LBB0_209
	s_waitcnt lgkmcnt(0)
	v_mov_b32_e32 v0, 0x3000
	global_load_dword v0, v0, s[2:3] offset:1280 sc1
	s_add_u32 s10, s2, 0x3500
	s_addc_u32 s11, s3, 0
	s_waitcnt vmcnt(0)
	v_cmp_eq_u32_e32 vcc, v0, v1
	s_and_saveexec_b64 s[8:9], vcc
	s_cbranch_execz .LBB0_208
	s_mov_b32 s14, 1
	s_mov_b64 s[12:13], 0
	v_mov_b32_e32 v0, 0
	s_branch .LBB0_199

; DI unsigned xb_ld(unsigned* p)              { return __hip_atomic_load(p, __ATOMIC_RELAXED, __HIP_MEMORY_SCOPE_AGENT); }
; DI unsigned xb_add(unsigned* p, unsigned v) { return __hip_atomic_fetch_add(p, v, __ATOMIC_RELAXED, __HIP_MEMORY_SCOPE_AGENT); }
; #define XB_SPIN(cond, bar) do { unsigned _sp = 0; while (cond) { __builtin_amdgcn_s_sleep(1); \
;     if ((++_sp & 255u) == 0u) { if (xb_ld(&(bar)[XB_TMO])) break; if (_sp > XB_SPIN_CAP) { atomicAdd(&(bar)[XB_TMO], 1u); break; } } } } while (0)
; DI void xcd_barrier(unsigned* bar, volatile LAS unsigned* st, bool leader) {
;     ...
;         const unsigned old = xb_add(&bar[XB_XSUB(x)], 1u);
;         const unsigned gen = old / nloc;
;         if (old + 1u == (gen + 1u) * nloc) {
;             __builtin_amdgcn_fence(__ATOMIC_RELEASE, "agent");
;             asm volatile("s_waitcnt vmcnt(0)" ::: "memory");
;             const unsigned og = xb_add(&bar[XB_TOP], 1u);
;             const unsigned tg = og / nx;
;             if (og + 1u == (tg + 1u) * nx) xb_add(&bar[XB_TOPGEN], 1u);
;             else XB_SPIN(xb_ld(&bar[XB_TOPGEN]) == tg, bar);
;             __builtin_amdgcn_fence(__ATOMIC_ACQUIRE, "agent");
;             xb_add(&bar[XB_XGEN(x)], 1u);
;             asm volatile("s_waitcnt vmcnt(0)" ::: "memory");
;         } else {
;             XB_SPIN(xb_ld(&bar[XB_XGEN(x)]) == gen, bar);
.LBB0_617:
	s_or_b64 exec, exec, s[8:9]
	v_cvt_f32_u32_e32 v4, v2
	s_waitcnt vmcnt(0)
	v_readfirstlane_b32 s6, v3
	v_sub_u32_e32 v3, 0, v2
	v_rcp_iflag_f32_e32 v4, v4
	v_add_u32_e32 v5, s6, v1
	v_mul_f32_e32 v4, 0x4f7ffffe, v4
	v_cvt_u32_f32_e32 v4, v4
	v_mul_lo_u32 v1, v3, v4
	v_mul_hi_u32 v1, v4, v1
	v_add_u32_e32 v1, v4, v1
	v_mul_hi_u32 v1, v5, v1
	v_mul_lo_u32 v3, v1, v2
	v_sub_u32_e32 v3, v5, v3
	v_add_u32_e32 v4, 1, v1
	v_cmp_ge_u32_e32 vcc, v3, v2
	s_nop 1
	v_cndmask_b32_e32 v1, v1, v4, vcc
	v_sub_u32_e32 v4, v3, v2
	v_cndmask_b32_e32 v3, v3, v4, vcc
	v_add_u32_e32 v4, 1, v1
	v_cmp_ge_u32_e32 vcc, v3, v2
	v_add_u32_e32 v3, 1, v5
	s_nop 0
	v_cndmask_b32_e32 v1, v1, v4, vcc
	v_mul_lo_u32 v4, v2, v1
	v_add_u32_e32 v2, v4, v2
	v_cmp_ne_u32_e32 vcc, v3, v2
	s_and_saveexec_b64 s[6:7], vcc
	s_xor_b64 s[6:7], exec, s[6:7]
	s_cbranch_execz .LBB0_631
	s_waitcnt lgkmcnt(0)
	v_mov_b32_e32 v0, 0x3000
	global_load_dword v0, v0, s[2:3] offset:1280 sc1
	s_add_u32 s10, s2, 0x3500
	s_addc_u32 s11, s3, 0
	s_waitcnt vmcnt(0)
	v_cmp_eq_u32_e32 vcc, v0, v1
	s_and_saveexec_b64 s[8:9], vcc
	s_cbranch_execz .LBB0_630
	s_mov_b32 s22, 1
	s_mov_b64 s[12:13], 0
	s_branch .LBB0_621
